# v64 + static priority: K-loop s_setprio flips deleted, one static s_setprio 1 for waves 0-3 (the leading half) at GEMM phase entry
# speedup vs baseline: 1.0050x; 1.0017x over previous
; __device__ __forceinline__ void convert_WA(const Ctx& F, int l) { convert_weights<false>(F, l); }
; __global__ void __launch_bounds__(512, 2) fwd_kernel(Params prm) {
;     ...
;     for (int ph = lo; ph < hi; ++ph) {
;         if (ph > lo) { if (lo < 0) cg::this_grid().sync(); else xcd_barrier(xbar); }
;         int wv_ = wave0; asm volatile("" : "+s"(wv_));
;         int ln_; asm volatile("v_mbcnt_lo_u32_b32 %0, -1, 0\n\tv_mbcnt_hi_u32_b32 %0, -1, %0" : "=v"(ln_));
;         F.wave = wv_; F.lane = ln_; F.tid = wv_ * 64 + ln_;
;         size_t wz_ = 0; asm volatile("" : "+s"(wz_));
;         unsigned char* ws = prm.ws + wz_;
;         float* MOD = (float*)(ws + OFF_MOD);
;         float* ctxres = (float*)(ws + OFF_CTX);
;         bf16_t* GRb = (bf16_t*)(ws + OFF_GR); bf16_t* Qb = (bf16_t*)(ws + OFF_Q); bf16_t* KVb = (bf16_t*)(ws + OFF_KV); bf16_t* GLb = (bf16_t*)(ws + OFF_GL);
;         bf16_t* RX = (bf16_t*)(ws + OFF_X); bf16_t* RY = (bf16_t*)(ws + OFF_Y);
;         bf16_t* A2 = (bf16_t*)(ws + OFF_A2); bf16_t* Fb = (bf16_t*)(ws + OFF_F); bf16_t* Mx = (bf16_t*)(ws + OFF_MX);
;         if (ph == 0) {
;             if (F.bid == F.G - 1) { float* TAB = (float*)(ws + OFF_TAB);
;                 for (int i = F.tid; i < 64 * 32; i += 512) { const int pos = i >> 5, f = i & 31; float sn, cs; sincosf((float)pos * exp2f(-(float)f * (13.287712379549449f / 32.0f)), &sn, &cs); TAB[2 * i] = cs; TAB[2 * i + 1] = sn; } }
;             mod_phase(F); __syncthreads(); convert_WA(F, 0); continue; }
;         if (ph == 1) { norm_phase<false, true>(F, MT, prm.in[0], prm.in[2], nullptr, nullptr, nullptr, nullptr, 0, nullptr, nullptr, prm.in[6], MOD, 1024, 0, RY); continue; }
;         const int l = (ph - 2) / 9, sp = (ph - 2) % 9;
;         const bool lastl = (l == 1);
;         bf16_t* Hl = l == 0 ? RY : RX; bf16_t* XRb = l == 0 ? RX : RY;
;         bf16_t* HF = Hl; bf16_t* Gb = XRb; bf16_t* H2 = RX;
;         const int Mg = lastl ? ML : MT;
;         const float* xres_lat = l == 0 ? prm.in[0] : prm.out; const float* xres_ctx = l == 0 ? prm.in[2] : ctxres;
;         const float* modl = MOD + (size_t)l * 5 * 6144;
;         switch (sp) {
.Lnrm_ret:
	v_readlane_b32 s73, v252, 7
	s_setprio 0
	s_mov_b32 s0, 0x6cb64
	s_bitcmp1_b32 s0, s72
	s_cbranch_scc0 .Lsp_done
	s_nop 3
	s_cmp_ge_u32 s73, 4
	s_cbranch_scc1 .Lsp_done
	s_setprio 1
